# prologue weight transposes rewritten: wave-private 64x64 tiles, 64 row loads in flight per wave, no LDS/barriers
# baseline (speedup 1.0000x reference)
; DI int logical_col(int n) { return (n & ~255) | (((n >> 5) & 3) << 6) | (((n >> 7) & 1) << 5) | (n & 31); }
; DI int colmap(int kind, int n) {
;   if (kind == 0 || kind == 3) n = logical_col(n);
;   if (kind == 0) { if (n < 1408) return n; if (n < 2688) return n + 32; if (n < 2720) return n - 2688 + 1408; return -1; }
;   if (kind == 1) { if (n >= 384) return -1; if (n < 256) return (n >> 6) * 96 + (n & 63); const int mm = n - 256; return (mm >> 5) * 96 + 64 + (mm & 31); }
;   if (kind == 2) { if (n < 256) return (n >> 6) * 128 + (n & 63); const int mm = n - 256; return (mm >> 6) * 128 + 64 + (mm & 63); }
;   return n;
; }
; DI void phase_prologue_a(char* lds, const Params& p, int bid, int nb) {
;   const int total = 2 * TR_PER_LAYER + 192 + 128;
;   for (int u = bid; u < total; u += nb) {
;     if (u < 2 * TR_PER_LAYER) {
;       const int l = u / TR_PER_LAYER; int r = u % TR_PER_LAYER;
;       if (r < 704) { transpose_tile(lds, p.w_in + (size_t)l * 1024 * 2720, 2720, nullptr, p.wt_in + (size_t)l * 2816 * 1024, 1024, 0, r >> 4, r & 15); continue; } r -= 704;
;       if (r < 256) { transpose_tile(lds, p.w_o + (size_t)l * 1024 * 1024, 1024, nullptr, p.wt_o + (size_t)l * 1024 * 1024, 1024, 3, r >> 4, r & 15); continue; } r -= 256;
;       if (r < 1024) { transpose_tile(lds, p.w_up + (size_t)l * 1024 * 4096, 4096, nullptr, p.wt_up + (size_t)l * 4096 * 1024, 1024, 3, r >> 4, r & 15); continue; } r -= 1024;
;       if (r < 1024) { transpose_tile(lds, p.w_down + (size_t)l * 4096 * 1024, 1024, nullptr, p.wt_down + (size_t)l * 1024 * 4096, 4096, 3, r >> 6, r & 63); continue; } r -= 1024;
;       if (r < 48) { transpose_tile(lds, p.mla_w_uq + (size_t)l * 384 * 384, 384, p.mla_q_norm_g + l * 384, p.wt_uq + (size_t)l * 512 * 384, 384, 1, r / 6, r % 6); continue; } r -= 48;
;       transpose_tile(lds, p.mla_w_ukv + (size_t)l * 256 * 512, 512, p.mla_kv_norm_g + l * 256, p.wt_ukv + (size_t)l * 512 * 256, 256, 2, r >> 2, r & 3);
_Z6k_mega6Params:
	s_load_dword s40, s[0:1], 0x168
	s_load_dwordx16 s[4:19], s[0:1], 0x0
	s_load_dwordx16 s[20:35], s[0:1], 0x40
	s_load_dwordx16 s[44:59], s[0:1], 0x80
	s_load_dwordx8 s[60:67], s[0:1], 0xc0
	s_load_dwordx2 s[36:37], s[0:1], 0x108
	v_and_b32_e32 v200, 0x3ff, v0
	v_and_b32_e32 v201, 63, v200
	v_lshrrev_b32_e32 v213, 5, v201
	v_and_b32_e32 v217, 31, v201
	v_lshl_or_b32 v202, v213, 6, v217
	v_mul_u32_u24_e32 v203, 0x60, v213
	v_add_u32_e32 v203, v203, v217
	v_mov_b32_e32 v215, 0
	v_mov_b32_e32 v211, 0
	s_waitcnt lgkmcnt(0)
	s_cmpk_lg_i32 s40, 0x100
	s_cbranch_scc1 .Ltr_end
	v_readfirstlane_b32 s41, v200
	s_nop 3
	s_lshr_b32 s41, s41, 6
	s_lshl_b32 s42, s2, 3
	s_add_i32 s41, s41, s42
	s_mov_b32 s43, 0
.Ltr_loop:
	s_lshl_b32 s68, s43, 11
	s_add_i32 s68, s68, s41
	s_cmpk_ge_i32 s68, 0xc10
	s_cselect_b32 s69, 1, 0
	s_cselect_b32 s70, 0xc10, 0
	s_sub_i32 s70, s68, s70
	s_mov_b32 s39, 0
	s_mov_b64 s[82:83], 0
	s_mov_b32 s38, 1
	s_cmpk_lt_i32 s70, 0x2c0
	s_cbranch_scc0 .Ltr_nA
	s_lshr_b32 s76, s70, 4
	s_and_b32 s77, s70, 15
	s_mov_b32 s75, 0
	s_movk_i32 s74, 10880
	s_movk_i32 s80, 2048
	s_mul_i32 s71, s69, 0xaa0000
	s_add_u32 s72, s12, s71
	s_addc_u32 s73, s13, 0
	s_mul_i32 s71, s69, 0x580000
	s_add_u32 s78, s54, s71
	s_addc_u32 s79, s55, 0
	s_branch .Ltr_lc
.Ltr_nA:
	s_cmpk_lt_i32 s70, 0x3c0
	s_cbranch_scc0 .Ltr_nB
	s_sub_i32 s71, s70, 0x2c0
	s_lshr_b32 s76, s71, 4
	s_and_b32 s77, s71, 15
	s_mov_b32 s75, 3
	s_movk_i32 s74, 4096
	s_movk_i32 s80, 2048
	s_mul_i32 s71, s69, 0x400000
	s_add_u32 s72, s14, s71
	s_addc_u32 s73, s15, 0
	s_mul_i32 s71, s69, 0x200000
	s_add_u32 s78, s56, s71
	s_addc_u32 s79, s57, 0
	s_branch .Ltr_lc
.Ltr_nB:
	s_cmpk_lt_i32 s70, 0x7c0
	s_cbranch_scc0 .Ltr_nC
	s_sub_i32 s71, s70, 0x3c0
	s_lshr_b32 s76, s71, 4
	s_and_b32 s77, s71, 15
	s_mov_b32 s75, 3
	s_movk_i32 s74, 16384
	s_movk_i32 s80, 2048
	s_mul_i32 s71, s69, 0x1000000
	s_add_u32 s72, s44, s71
	s_addc_u32 s73, s45, 0
	s_mul_i32 s71, s69, 0x800000
	s_add_u32 s78, s58, s71
	s_addc_u32 s79, s59, 0
	s_branch .Ltr_lc
.Ltr_nC:
	s_cmpk_lt_i32 s70, 0xbc0
	s_cbranch_scc0 .Ltr_nD
	s_sub_i32 s71, s70, 0x7c0
	s_lshr_b32 s76, s71, 6
	s_and_b32 s77, s71, 63
	s_mov_b32 s75, 3
	s_movk_i32 s74, 4096
	s_movk_i32 s80, 8192
	s_mul_i32 s71, s69, 0x1000000
	s_add_u32 s72, s46, s71
	s_addc_u32 s73, s47, 0
	s_mul_i32 s71, s69, 0x800000
	s_add_u32 s78, s60, s71
	s_addc_u32 s79, s61, 0
	s_branch .Ltr_lc
.Ltr_nD:
	s_cmpk_lt_i32 s70, 0xbf0
	s_cbranch_scc0 .Ltr_nE
	s_sub_i32 s71, s70, 0xbc0
	s_mul_i32 s76, s71, 43
	s_lshr_b32 s76, s76, 8
	s_mul_i32 s77, s76, 6
	s_sub_i32 s77, s71, s77
	s_mov_b32 s75, 1
	s_movk_i32 s74, 1536
	s_movk_i32 s80, 768
	s_mul_i32 s71, s69, 0x90000
	s_add_u32 s72, s22, s71
	s_addc_u32 s73, s23, 0
	s_mul_i32 s71, s69, 0x60000
	s_add_u32 s78, s62, s71
	s_addc_u32 s79, s63, 0
	s_mul_i32 s71, s69, 1536
	s_add_u32 s82, s20, s71
	s_addc_u32 s83, s21, 0
	s_mov_b32 s38, 0
	s_mul_i32 s81, s76, 0x60
	s_cmp_lt_u32 s76, 4
	s_cbranch_scc1 .Ltr_common
	s_sub_i32 s81, s76, 4
	s_mul_i32 s81, s81, 0xc0
	s_add_i32 s81, s81, 64
	s_mov_b32 s38, 2
	s_cmp_lt_u32 s76, 6
	s_cbranch_scc1 .Ltr_common
	s_mov_b32 s39, 1
	s_mov_b32 s81, 0
	s_mov_b32 s38, 0
	s_branch .Ltr_common
.Ltr_nE:
	s_sub_i32 s71, s70, 0xbf0
	s_lshr_b32 s76, s71, 2
	s_and_b32 s77, s71, 3
	s_mov_b32 s75, 2
	s_movk_i32 s74, 2048
	s_movk_i32 s80, 512
	s_mul_i32 s71, s69, 0x80000
	s_add_u32 s72, s26, s71
	s_addc_u32 s73, s27, 0
	s_mul_i32 s71, s69, 0x40000
	s_add_u32 s78, s64, s71
	s_addc_u32 s79, s65, 0
	s_mul_i32 s71, s69, 1024
	s_add_u32 s82, s24, s71
	s_addc_u32 s83, s25, 0
	s_mov_b32 s38, 0
	s_lshl_b32 s81, s76, 7
	s_cmp_lt_u32 s76, 4
	s_cbranch_scc1 .Ltr_common
	s_sub_i32 s81, s76, 4
	s_lshl_b32 s81, s81, 7
	s_add_i32 s81, s81, 64
	s_branch .Ltr_common
.Ltr_lc:
	s_lshr_b32 s81, s76, 2
	s_lshl_b32 s81, s81, 8
	s_and_b32 s71, s76, 1
	s_lshl_b32 s71, s71, 7
	s_or_b32 s81, s81, s71
	s_bfe_u32 s71, s76, 0x10001
	s_lshl_b32 s71, s71, 5
	s_or_b32 s81, s81, s71
.Ltr_common:
	s_mul_i32 s71, s77, s74
	s_lshl_b32 s71, s71, 6
	s_add_u32 s72, s72, s71
	s_addc_u32 s73, s73, 0
	s_lshl_b32 s71, s77, 7
	s_add_u32 s78, s78, s71
	s_addc_u32 s79, s79, 0
	v_mov_b32_e32 v212, v201
	s_cmp_eq_u32 s38, 0
	s_cbranch_scc1 .Ltr_lsel
	v_mov_b32_e32 v212, v202
	s_cmp_eq_u32 s38, 1
	s_cbranch_scc1 .Ltr_lsel
	v_mov_b32_e32 v212, v203
.Ltr_lsel:
	v_add_u32_e32 v212, s81, v212
	s_cmp_lg_u32 s75, 0
	s_cbranch_scc1 .Ltr_nofix
	s_movk_i32 s71, 0x580
	v_cmp_le_u32_e32 vcc, s71, v212
	s_nop 1
	v_cndmask_b32_e64 v213, 0, 32, vcc
	v_mov_b32_e32 v217, 0xfffffb00
	s_movk_i32 s71, 0xa80
	v_cmp_le_u32_e32 vcc, s71, v212
	s_nop 1
	v_cndmask_b32_e32 v213, v213, v217, vcc
	s_movk_i32 s71, 0xaa0
	v_cmp_le_u32_e64 s[100:101], s71, v212
	v_add_u32_e32 v212, v212, v213
	s_branch .Ltr_addr
.Ltr_nofix:
	s_mov_b64 s[100:101], 0
	s_cmp_eq_u32 s39, 0
	s_cbranch_scc1 .Ltr_addr
	s_mov_b64 s[100:101], -1
; DI int tidx() { int t = __builtin_amdgcn_workitem_id_x(); asm volatile("" : "+v"(t)); return t; }
; DI void transpose_tile(char* lds, const float* __restrict__ in, int ldin, const float* __restrict__ scale, bf16_t* __restrict__ out, int Kdim, int kind, int nt, int kt) {
;   float* tile = (float*)lds;
;   const int tid = tidx(), n0 = nt * 64, k0 = kt * 64;
;   {
;     const int nl = (tid & 15) * 4, col = colmap(kind, n0 + nl);
; #pragma unroll
;     for (int rr = 0; rr < 2; ++rr) { const int kl = rr * 32 + (tid >> 4);
;       f32x4 v = {0.f, 0.f, 0.f, 0.f}; if (col >= 0) { v = *(const f32x4*)(in + (size_t)(k0 + kl) * ldin + col); if (scale) v *= scale[k0 + kl]; }
;       float* t = tile + kl * 65 + nl; t[0] = v[0]; t[1] = v[1]; t[2] = v[2]; t[3] = v[3]; }
.Ltr_addr:
	v_mov_b32_e32 v214, v212
	v_lshl_add_u64 v[204:205], v[214:215], 2, s[72:73]
	v_mov_b32_e32 v213, s36
	v_mov_b32_e32 v217, s37
	v_cndmask_b32_e64 v204, v204, v213, s[100:101]
	v_cndmask_b32_e64 v205, v205, v217, s[100:101]
	v_mov_b32_e32 v213, s74
	v_cndmask_b32_e64 v210, v213, 0, s[100:101]
	v_lshl_add_u32 v216, s76, 6, v201
	v_mul_lo_u32 v214, v216, s80
	v_lshl_add_u64 v[208:209], v[214:215], 0, s[78:79]
	global_load_dword v100, v[204:205], off
	v_lshl_add_u64 v[204:205], v[204:205], 0, v[210:211]
	global_load_dword v101, v[204:205], off
	v_lshl_add_u64 v[204:205], v[204:205], 0, v[210:211]
	global_load_dword v102, v[204:205], off
	v_lshl_add_u64 v[204:205], v[204:205], 0, v[210:211]
	global_load_dword v103, v[204:205], off
	v_lshl_add_u64 v[204:205], v[204:205], 0, v[210:211]
	global_load_dword v104, v[204:205], off
	v_lshl_add_u64 v[204:205], v[204:205], 0, v[210:211]
	global_load_dword v105, v[204:205], off
	v_lshl_add_u64 v[204:205], v[204:205], 0, v[210:211]
	global_load_dword v106, v[204:205], off
	v_lshl_add_u64 v[204:205], v[204:205], 0, v[210:211]
	global_load_dword v107, v[204:205], off
	v_lshl_add_u64 v[204:205], v[204:205], 0, v[210:211]
	global_load_dword v108, v[204:205], off
	v_lshl_add_u64 v[204:205], v[204:205], 0, v[210:211]
	global_load_dword v109, v[204:205], off
	v_lshl_add_u64 v[204:205], v[204:205], 0, v[210:211]
	global_load_dword v110, v[204:205], off
	v_lshl_add_u64 v[204:205], v[204:205], 0, v[210:211]
	global_load_dword v111, v[204:205], off
	v_lshl_add_u64 v[204:205], v[204:205], 0, v[210:211]
	global_load_dword v112, v[204:205], off
	v_lshl_add_u64 v[204:205], v[204:205], 0, v[210:211]
	global_load_dword v113, v[204:205], off
	v_lshl_add_u64 v[204:205], v[204:205], 0, v[210:211]
	global_load_dword v114, v[204:205], off
	v_lshl_add_u64 v[204:205], v[204:205], 0, v[210:211]
	global_load_dword v115, v[204:205], off
	v_lshl_add_u64 v[204:205], v[204:205], 0, v[210:211]
	global_load_dword v116, v[204:205], off
	v_lshl_add_u64 v[204:205], v[204:205], 0, v[210:211]
	global_load_dword v117, v[204:205], off
	v_lshl_add_u64 v[204:205], v[204:205], 0, v[210:211]
	global_load_dword v118, v[204:205], off
	v_lshl_add_u64 v[204:205], v[204:205], 0, v[210:211]
	global_load_dword v119, v[204:205], off
	v_lshl_add_u64 v[204:205], v[204:205], 0, v[210:211]
	global_load_dword v120, v[204:205], off
	v_lshl_add_u64 v[204:205], v[204:205], 0, v[210:211]
	global_load_dword v121, v[204:205], off
	v_lshl_add_u64 v[204:205], v[204:205], 0, v[210:211]
	global_load_dword v122, v[204:205], off
	v_lshl_add_u64 v[204:205], v[204:205], 0, v[210:211]
	global_load_dword v123, v[204:205], off
	v_lshl_add_u64 v[204:205], v[204:205], 0, v[210:211]
	global_load_dword v124, v[204:205], off
	v_lshl_add_u64 v[204:205], v[204:205], 0, v[210:211]
	global_load_dword v125, v[204:205], off
	v_lshl_add_u64 v[204:205], v[204:205], 0, v[210:211]
	global_load_dword v126, v[204:205], off
	v_lshl_add_u64 v[204:205], v[204:205], 0, v[210:211]
	global_load_dword v127, v[204:205], off
	v_lshl_add_u64 v[204:205], v[204:205], 0, v[210:211]
	global_load_dword v128, v[204:205], off
	v_lshl_add_u64 v[204:205], v[204:205], 0, v[210:211]
	global_load_dword v129, v[204:205], off
	v_lshl_add_u64 v[204:205], v[204:205], 0, v[210:211]
	global_load_dword v130, v[204:205], off
	v_lshl_add_u64 v[204:205], v[204:205], 0, v[210:211]
	global_load_dword v131, v[204:205], off
	v_lshl_add_u64 v[204:205], v[204:205], 0, v[210:211]
	global_load_dword v132, v[204:205], off
	v_lshl_add_u64 v[204:205], v[204:205], 0, v[210:211]
	global_load_dword v133, v[204:205], off
	v_lshl_add_u64 v[204:205], v[204:205], 0, v[210:211]
	global_load_dword v134, v[204:205], off
	v_lshl_add_u64 v[204:205], v[204:205], 0, v[210:211]
	global_load_dword v135, v[204:205], off
	v_lshl_add_u64 v[204:205], v[204:205], 0, v[210:211]
	global_load_dword v136, v[204:205], off
	v_lshl_add_u64 v[204:205], v[204:205], 0, v[210:211]
	global_load_dword v137, v[204:205], off
	v_lshl_add_u64 v[204:205], v[204:205], 0, v[210:211]
	global_load_dword v138, v[204:205], off
	v_lshl_add_u64 v[204:205], v[204:205], 0, v[210:211]
	global_load_dword v139, v[204:205], off
	v_lshl_add_u64 v[204:205], v[204:205], 0, v[210:211]
	global_load_dword v140, v[204:205], off
	v_lshl_add_u64 v[204:205], v[204:205], 0, v[210:211]
	global_load_dword v141, v[204:205], off
	v_lshl_add_u64 v[204:205], v[204:205], 0, v[210:211]
	global_load_dword v142, v[204:205], off
	v_lshl_add_u64 v[204:205], v[204:205], 0, v[210:211]
	global_load_dword v143, v[204:205], off
	v_lshl_add_u64 v[204:205], v[204:205], 0, v[210:211]
	global_load_dword v144, v[204:205], off
	v_lshl_add_u64 v[204:205], v[204:205], 0, v[210:211]
	global_load_dword v145, v[204:205], off
	v_lshl_add_u64 v[204:205], v[204:205], 0, v[210:211]
	global_load_dword v146, v[204:205], off
	v_lshl_add_u64 v[204:205], v[204:205], 0, v[210:211]
	global_load_dword v147, v[204:205], off
	v_lshl_add_u64 v[204:205], v[204:205], 0, v[210:211]
	global_load_dword v148, v[204:205], off
	v_lshl_add_u64 v[204:205], v[204:205], 0, v[210:211]
	global_load_dword v149, v[204:205], off
	v_lshl_add_u64 v[204:205], v[204:205], 0, v[210:211]
	global_load_dword v150, v[204:205], off
	v_lshl_add_u64 v[204:205], v[204:205], 0, v[210:211]
	global_load_dword v151, v[204:205], off
	v_lshl_add_u64 v[204:205], v[204:205], 0, v[210:211]
	global_load_dword v152, v[204:205], off
	v_lshl_add_u64 v[204:205], v[204:205], 0, v[210:211]
	global_load_dword v153, v[204:205], off
	v_lshl_add_u64 v[204:205], v[204:205], 0, v[210:211]
	global_load_dword v154, v[204:205], off
	v_lshl_add_u64 v[204:205], v[204:205], 0, v[210:211]
	global_load_dword v155, v[204:205], off
	v_lshl_add_u64 v[204:205], v[204:205], 0, v[210:211]
	global_load_dword v156, v[204:205], off
	v_lshl_add_u64 v[204:205], v[204:205], 0, v[210:211]
	global_load_dword v157, v[204:205], off
	v_lshl_add_u64 v[204:205], v[204:205], 0, v[210:211]
	global_load_dword v158, v[204:205], off
	v_lshl_add_u64 v[204:205], v[204:205], 0, v[210:211]
	global_load_dword v159, v[204:205], off
	v_lshl_add_u64 v[204:205], v[204:205], 0, v[210:211]
	global_load_dword v160, v[204:205], off
	v_lshl_add_u64 v[204:205], v[204:205], 0, v[210:211]
	global_load_dword v161, v[204:205], off
	v_lshl_add_u64 v[204:205], v[204:205], 0, v[210:211]
	global_load_dword v162, v[204:205], off
	v_lshl_add_u64 v[204:205], v[204:205], 0, v[210:211]
	global_load_dword v163, v[204:205], off
	v_lshl_add_u64 v[204:205], v[204:205], 0, v[210:211]
	s_cmp_eq_u64 s[82:83], 0
	s_cbranch_scc1 .Ltr_nosc
; DI unsigned pk2(float a, float b) { f32x2 v = {a, b}; bf2_t r = __builtin_convertvector(v, bf2_t); return __builtin_bit_cast(unsigned, r); }
; DI void transpose_tile(char* lds, const float* __restrict__ in, int ldin, const float* __restrict__ scale, bf16_t* __restrict__ out, int Kdim, int kind, int nt, int kt) {
;     ...
;       f32x4 v = {0.f, 0.f, 0.f, 0.f}; if (col >= 0) { v = *(const f32x4*)(in + (size_t)(k0 + kl) * ldin + col); if (scale) v *= scale[k0 + kl]; }
;       float* t = tile + kl * 65 + nl; t[0] = v[0]; t[1] = v[1]; t[2] = v[2]; t[3] = v[3]; }
;   }
;   __syncthreads();
;   {
;     const int nl = tid >> 3, kc = (tid & 7) * 8;
;     float v[8];
; #pragma unroll
;     for (int e = 0; e < 8; ++e) v[e] = tile[(kc + e) * 65 + nl];
;     bf16_t* dst = out + (size_t)(n0 + nl) * Kdim + k0 + kc;
;     u32x4 w0 = {pk2(v[0], v[1]), pk2(v[2], v[3]), pk2(v[4], v[5]), pk2(v[6], v[7])};
;     *(u32x4*)dst = w0;
;   }
	s_lshl_b32 s71, s77, 8
	s_add_u32 s82, s82, s71
	s_addc_u32 s83, s83, 0
	s_waitcnt vmcnt(0)
	s_load_dwordx16 s[84:99], s[82:83], 0x0
	s_waitcnt lgkmcnt(0)
	v_mul_f32_e32 v100, s84, v100
	v_mul_f32_e32 v101, s85, v101
	v_mul_f32_e32 v102, s86, v102
	v_mul_f32_e32 v103, s87, v103
	v_mul_f32_e32 v104, s88, v104
	v_mul_f32_e32 v105, s89, v105
	v_mul_f32_e32 v106, s90, v106
	v_mul_f32_e32 v107, s91, v107
	v_mul_f32_e32 v108, s92, v108
	v_mul_f32_e32 v109, s93, v109
	v_mul_f32_e32 v110, s94, v110
	v_mul_f32_e32 v111, s95, v111
	v_mul_f32_e32 v112, s96, v112
	v_mul_f32_e32 v113, s97, v113
	v_mul_f32_e32 v114, s98, v114
	v_mul_f32_e32 v115, s99, v115
	s_load_dwordx16 s[84:99], s[82:83], 0x40
	s_waitcnt lgkmcnt(0)
	v_mul_f32_e32 v116, s84, v116
	v_mul_f32_e32 v117, s85, v117
	v_mul_f32_e32 v118, s86, v118
	v_mul_f32_e32 v119, s87, v119
	v_mul_f32_e32 v120, s88, v120
	v_mul_f32_e32 v121, s89, v121
	v_mul_f32_e32 v122, s90, v122
	v_mul_f32_e32 v123, s91, v123
	v_mul_f32_e32 v124, s92, v124
	v_mul_f32_e32 v125, s93, v125
	v_mul_f32_e32 v126, s94, v126
	v_mul_f32_e32 v127, s95, v127
	v_mul_f32_e32 v128, s96, v128
	v_mul_f32_e32 v129, s97, v129
	v_mul_f32_e32 v130, s98, v130
	v_mul_f32_e32 v131, s99, v131
	s_load_dwordx16 s[84:99], s[82:83], 0x80
	s_waitcnt lgkmcnt(0)
	v_mul_f32_e32 v132, s84, v132
	v_mul_f32_e32 v133, s85, v133
	v_mul_f32_e32 v134, s86, v134
	v_mul_f32_e32 v135, s87, v135
	v_mul_f32_e32 v136, s88, v136
	v_mul_f32_e32 v137, s89, v137
	v_mul_f32_e32 v138, s90, v138
	v_mul_f32_e32 v139, s91, v139
	v_mul_f32_e32 v140, s92, v140
	v_mul_f32_e32 v141, s93, v141
	v_mul_f32_e32 v142, s94, v142
	v_mul_f32_e32 v143, s95, v143
	v_mul_f32_e32 v144, s96, v144
	v_mul_f32_e32 v145, s97, v145
	v_mul_f32_e32 v146, s98, v146
	v_mul_f32_e32 v147, s99, v147
	s_load_dwordx16 s[84:99], s[82:83], 0xc0
	s_waitcnt lgkmcnt(0)
	v_mul_f32_e32 v148, s84, v148
	v_mul_f32_e32 v149, s85, v149
	v_mul_f32_e32 v150, s86, v150
	v_mul_f32_e32 v151, s87, v151
	v_mul_f32_e32 v152, s88, v152
	v_mul_f32_e32 v153, s89, v153
	v_mul_f32_e32 v154, s90, v154
	v_mul_f32_e32 v155, s91, v155
	v_mul_f32_e32 v156, s92, v156
	v_mul_f32_e32 v157, s93, v157
	v_mul_f32_e32 v158, s94, v158
	v_mul_f32_e32 v159, s95, v159
	v_mul_f32_e32 v160, s96, v160
	v_mul_f32_e32 v161, s97, v161
	v_mul_f32_e32 v162, s98, v162
	v_mul_f32_e32 v163, s99, v163
.Ltr_nosc:
	s_waitcnt vmcnt(0)
	v_cvt_pk_bf16_f32 v170, v100, v101
	v_cvt_pk_bf16_f32 v171, v102, v103
	v_cvt_pk_bf16_f32 v172, v104, v105
	v_cvt_pk_bf16_f32 v173, v106, v107
	global_store_dwordx4 v[208:209], v[170:173], off
	v_cvt_pk_bf16_f32 v174, v108, v109
	v_cvt_pk_bf16_f32 v175, v110, v111
	v_cvt_pk_bf16_f32 v176, v112, v113
	v_cvt_pk_bf16_f32 v177, v114, v115
	global_store_dwordx4 v[208:209], v[174:177], off offset:16
	v_cvt_pk_bf16_f32 v170, v116, v117
	v_cvt_pk_bf16_f32 v171, v118, v119
	v_cvt_pk_bf16_f32 v172, v120, v121
	v_cvt_pk_bf16_f32 v173, v122, v123
	global_store_dwordx4 v[208:209], v[170:173], off offset:32
	v_cvt_pk_bf16_f32 v174, v124, v125
	v_cvt_pk_bf16_f32 v175, v126, v127
	v_cvt_pk_bf16_f32 v176, v128, v129
	v_cvt_pk_bf16_f32 v177, v130, v131
	global_store_dwordx4 v[208:209], v[174:177], off offset:48
	v_cvt_pk_bf16_f32 v170, v132, v133
	v_cvt_pk_bf16_f32 v171, v134, v135
	v_cvt_pk_bf16_f32 v172, v136, v137
	v_cvt_pk_bf16_f32 v173, v138, v139
	global_store_dwordx4 v[208:209], v[170:173], off offset:64
	v_cvt_pk_bf16_f32 v174, v140, v141
	v_cvt_pk_bf16_f32 v175, v142, v143
	v_cvt_pk_bf16_f32 v176, v144, v145
	v_cvt_pk_bf16_f32 v177, v146, v147
	global_store_dwordx4 v[208:209], v[174:177], off offset:80
	v_cvt_pk_bf16_f32 v170, v148, v149
	v_cvt_pk_bf16_f32 v171, v150, v151
	v_cvt_pk_bf16_f32 v172, v152, v153
	v_cvt_pk_bf16_f32 v173, v154, v155
	global_store_dwordx4 v[208:209], v[170:173], off offset:96
	v_cvt_pk_bf16_f32 v174, v156, v157
	v_cvt_pk_bf16_f32 v175, v158, v159
	v_cvt_pk_bf16_f32 v176, v160, v161
	v_cvt_pk_bf16_f32 v177, v162, v163
	global_store_dwordx4 v[208:209], v[174:177], off offset:112
	s_add_i32 s43, s43, 1
	s_cmp_lt_u32 s43, 3
	s_cbranch_scc1 .Ltr_loop
	s_waitcnt vmcnt(0)
; #define LAS __attribute__((address_space(3)))
; DI void phase_prologue_a(char* lds, const Params& p, int bid, int nb) {
;   const int total = 2 * TR_PER_LAYER + 192 + 128;
;   for (int u = bid; u < total; u += nb) {
;     if (u < 2 * TR_PER_LAYER) {
;       const int l = u / TR_PER_LAYER; int r = u % TR_PER_LAYER;
;       if (r < 704) { transpose_tile(lds, p.w_in + (size_t)l * 1024 * 2720, 2720, nullptr, p.wt_in + (size_t)l * 2816 * 1024, 1024, 0, r >> 4, r & 15); continue; } r -= 704;
;       if (r < 256) { transpose_tile(lds, p.w_o + (size_t)l * 1024 * 1024, 1024, nullptr, p.wt_o + (size_t)l * 1024 * 1024, 1024, 3, r >> 4, r & 15); continue; } r -= 256;
;       if (r < 1024) { transpose_tile(lds, p.w_up + (size_t)l * 1024 * 4096, 4096, nullptr, p.wt_up + (size_t)l * 4096 * 1024, 1024, 3, r >> 4, r & 15); continue; } r -= 1024;
;       if (r < 1024) { transpose_tile(lds, p.w_down + (size_t)l * 4096 * 1024, 1024, nullptr, p.wt_down + (size_t)l * 1024 * 4096, 4096, 3, r >> 6, r & 63); continue; } r -= 1024;
;       if (r < 48) { transpose_tile(lds, p.mla_w_uq + (size_t)l * 384 * 384, 384, p.mla_q_norm_g + l * 384, p.wt_uq + (size_t)l * 512 * 384, 384, 1, r / 6, r % 6); continue; } r -= 48;
;       transpose_tile(lds, p.mla_w_ukv + (size_t)l * 256 * 512, 512, p.mla_kv_norm_g + l * 256, p.wt_ukv + (size_t)l * 512 * 256, 256, 2, r >> 2, r & 3);
;     } else if (u < 2 * TR_PER_LAYER + 192) {
;       const int r = u - 2 * TR_PER_LAYER, kc = r & 7, jb = (r >> 3) % 12, l = r / 96;
;       float* sl = (float*)lds;
; #pragma unroll
;       for (int e = 0; e < 2; ++e) { const int i = tidx() + 512 * e, bb = i >> 7, k = i & 127; const float cv = p.c[bb * 1024 + kc * 128 + k]; sl[i] = cv / (1.f + expf(-cv)); }
;       __syncthreads();
;       const int j = jb * 512 + tidx();
;       float a0 = 0.f, a1 = 0.f, a2 = 0.f, a3 = 0.f, a4 = 0.f, a5 = 0.f, a6 = 0.f, a7 = 0.f;
;       const float* w = p.w_ada + ((size_t)l * 1024 + kc * 128) * 6144 + j;
; #pragma unroll 4
; __global__ void __launch_bounds__(512) k_mega(Params p) {
;   __shared__ __attribute__((aligned(16))) char smem[LDS_BYTES + 8 * EPI8_IMG + 64];
;   cg::grid_group grid = cg::this_grid();
;   volatile LAS unsigned* st = (volatile LAS unsigned*)(LAS char*)(smem + LDS_BYTES + 8 * EPI8_IMG);
;   if (threadIdx.x < 2) st[threadIdx.x] = 0u;
;   __syncthreads();
;   const XcdBarrier xb = xcd_barrier_post(p.bar, st);
.Ltr_end:
	s_load_dwordx16 s[4:19], s[0:1], 0x100
	s_mov_b32 s36, s2
	s_load_dword s2, s[0:1], 0x170
	s_load_dwordx2 s[96:97], s[0:1], 0x168
	v_and_b32_e32 v206, 0x3ff, v0
	s_waitcnt lgkmcnt(0)
	v_writelane_b32 v252, s4, 0
	v_cmp_gt_u32_e32 vcc, 2, v206
	s_nop 0
	v_writelane_b32 v252, s5, 1
	v_writelane_b32 v252, s6, 2
	v_writelane_b32 v252, s7, 3
	v_writelane_b32 v252, s8, 4
	v_writelane_b32 v252, s9, 5
	v_writelane_b32 v252, s10, 6
	v_writelane_b32 v252, s11, 7
	v_writelane_b32 v252, s12, 8
	v_writelane_b32 v252, s13, 9
	v_writelane_b32 v252, s14, 10
	v_writelane_b32 v252, s15, 11
	v_writelane_b32 v252, s16, 12
	v_writelane_b32 v252, s17, 13
	v_writelane_b32 v252, s18, 14
	v_writelane_b32 v252, s19, 15
	v_writelane_b32 v252, s2, 16
	s_add_u32 s2, s0, 0x168
	s_addc_u32 s3, s1, 0
	s_and_saveexec_b64 s[4:5], vcc
	v_mov_b32_e32 v1, 0x24800
	v_lshl_add_u32 v1, v206, 2, v1
	v_mov_b32_e32 v2, 0
	ds_write_b32 v1, v2
	s_or_b64 exec, exec, s[4:5]
	s_load_dwordx16 s[68:83], s[0:1], 0x80
	s_load_dwordx16 s[4:19], s[0:1], 0xc0
	s_waitcnt lgkmcnt(0)
	s_barrier
	v_writelane_b32 v252, s4, 17
	s_nop 1
	v_writelane_b32 v252, s5, 18
	v_writelane_b32 v252, s6, 19
	v_writelane_b32 v252, s7, 20
	v_writelane_b32 v252, s8, 21
	v_writelane_b32 v252, s9, 22
	v_writelane_b32 v252, s10, 23
	v_writelane_b32 v252, s11, 24
	v_writelane_b32 v252, s12, 25
	v_writelane_b32 v252, s13, 26
	v_writelane_b32 v252, s14, 27
	v_writelane_b32 v252, s15, 28
	v_writelane_b32 v252, s16, 29
	v_writelane_b32 v252, s17, 30
	v_writelane_b32 v252, s18, 31
	v_writelane_b32 v252, s19, 32
	s_getreg_b32 s4, hwreg(HW_REG_XCC_ID, 0, 4)
	s_and_b32 s4, s4, 15
	v_writelane_b32 v252, s4, 33
	v_cmp_eq_u32_e64 s[6:7], 0, v206
	s_mov_b64 s[4:5], exec
	s_nop 0
	v_writelane_b32 v252, s6, 34
	s_nop 1
	v_writelane_b32 v252, s7, 35
	s_and_b64 s[6:7], s[4:5], s[6:7]
	s_mov_b64 exec, s[6:7]
	s_cbranch_execz .LBB0_5
	s_mov_b64 s[6:7], exec
	v_mbcnt_lo_u32_b32 v1, s6, 0
	v_mbcnt_hi_u32_b32 v1, s7, v1
	v_cmp_eq_u32_e32 vcc, 0, v1
	s_and_b64 s[8:9], exec, vcc
	s_mov_b64 exec, s[8:9]
	s_cbranch_execz .LBB0_5
	v_readlane_b32 s8, v252, 33
	s_lshl_b32 s8, s8, 8
	s_bcnt1_i32_b64 s6, s[6:7]
	v_mov_b32_e32 v1, s8
	s_load_dwordx16 s[8:23], s[0:1], 0x100
	v_mov_b32_e32 v2, s6
	s_waitcnt lgkmcnt(0)
	global_atomic_add v1, v2, s[10:11] offset:1024
.LBB0_5:
	s_or_b64 exec, exec, s[4:5]
	s_load_dwordx2 s[94:95], s[0:1], 0x160
	s_load_dwordx8 s[4:11], s[0:1], 0x140
	s_cmpk_gt_i32 s36, 0x195f
	s_waitcnt lgkmcnt(0)
	v_writelane_b32 v252, s4, 36
	s_nop 1
	v_writelane_b32 v252, s5, 37
	v_writelane_b32 v252, s6, 38
	v_writelane_b32 v252, s7, 39
	v_writelane_b32 v252, s8, 40
	v_writelane_b32 v252, s9, 41
	v_writelane_b32 v252, s10, 42
	v_writelane_b32 v252, s11, 43
	s_load_dwordx16 s[4:19], s[0:1], 0x0
	s_waitcnt lgkmcnt(0)
	v_writelane_b32 v252, s4, 44
	s_nop 1
	v_writelane_b32 v252, s5, 45
	v_writelane_b32 v252, s6, 46
	v_writelane_b32 v252, s7, 47
	v_writelane_b32 v252, s8, 48
	v_writelane_b32 v252, s9, 49
	v_writelane_b32 v252, s10, 50
	v_writelane_b32 v252, s11, 51
	v_writelane_b32 v252, s12, 52
	v_writelane_b32 v252, s13, 53
	v_writelane_b32 v252, s14, 54
	v_writelane_b32 v252, s15, 55
	v_writelane_b32 v252, s16, 56
	v_writelane_b32 v252, s17, 57
	v_writelane_b32 v252, s18, 58
	v_writelane_b32 v252, s19, 59
	s_load_dwordx16 s[4:19], s[0:1], 0x40
	s_waitcnt lgkmcnt(0)
	v_writelane_b32 v252, s4, 60
	s_nop 1
	v_writelane_b32 v251, s8, 0
	v_writelane_b32 v251, s9, 1
	v_writelane_b32 v251, s10, 2
	v_writelane_b32 v251, s11, 3
	v_writelane_b32 v251, s12, 4
	v_writelane_b32 v251, s13, 5
	v_writelane_b32 v251, s14, 6
	v_writelane_b32 v251, s15, 7
	v_writelane_b32 v251, s16, 8
	v_writelane_b32 v252, s5, 61
	v_writelane_b32 v251, s17, 9
	v_writelane_b32 v252, s6, 62
	v_writelane_b32 v251, s18, 10
	v_writelane_b32 v252, s7, 63
	v_writelane_b32 v251, s19, 11
	s_cbranch_scc1 .LBB0_70
	v_readlane_b32 s4, v252, 60
	v_readlane_b32 s8, v251, 0
	v_readlane_b32 s9, v251, 1
	v_readlane_b32 s5, v252, 61
	v_readlane_b32 s6, v252, 62
	v_readlane_b32 s7, v252, 63
	s_cmp_lg_u64 s[8:9], 0
	v_readlane_b32 s10, v251, 2
	v_readlane_b32 s11, v251, 3
	v_readlane_b32 s12, v251, 4
	v_readlane_b32 s13, v251, 5
	v_readlane_b32 s14, v251, 6
	v_readlane_b32 s15, v251, 7
	s_cselect_b64 s[6:7], -1, 0
	s_cmp_lg_u64 s[4:5], 0
	s_mov_b32 s10, 0x3c1c381e
	s_mov_b32 s12, 0x6dc9c883
	s_mov_b32 s14, 0x54442d18
	s_mov_b32 s34, 0x13a86d09
	s_mov_b32 s44, 0xa8c07c9d
	s_cselect_b64 s[0:1], -1, 0
	s_mov_b32 s9, 0
	s_mov_b32 s11, 0x3fe1feb3
	s_mov_b32 s13, 0x3fc45f30
	s_mov_b32 s15, 0xc01921fb
	s_mov_b32 s35, 0x3de61246
	s_mov_b32 s45, 0xbda93974
	s_mov_b32 s33, 0xbfb8aa3b
	s_mov_b32 s52, 0x42ce8ed0
	s_mov_b32 s53, 0xc2b17218
	v_mov_b32_e32 v35, 0
	v_cndmask_b32_e64 v1, 0, 1, s[6:7]
	s_movk_i32 s54, 0x104
	s_movk_i32 s55, 0x600
	s_movk_i32 s56, 0xff1c
	s_movk_i32 s57, 0x2a80
	v_mov_b32_e32 v36, 0x67f544e4
	v_mov_b32_e32 v37, 0xbe5ae645
	v_mov_b32_e32 v38, 0xa556c734
	v_mov_b32_e32 v39, 0x3ec71de3
	v_mov_b32_e32 v40, 0x1a01a01a
	v_mov_b32_e32 v41, 0xbf2a01a0
	v_mov_b32_e32 v42, 0x11111111
	v_mov_b32_e32 v43, 0x3f811111
	v_mov_b32_e32 v44, 0x55555555
	v_mov_b32_e32 v45, 0xbfc55555
	v_mov_b32_e32 v46, 0xeff8d898
	v_mov_b32_e32 v47, 0x3e21eed8
	v_mov_b32_e32 v48, 0xb7789f5c
	v_mov_b32_e32 v49, 0xbe927e4f
	v_mov_b32_e32 v51, 0x3efa01a0
	v_mov_b32_e32 v52, 0x16c16c17
	v_mov_b32_e32 v53, 0xbf56c16c
	v_mov_b32_e32 v55, 0x3fa55555
	v_mov_b32_e32 v64, 0x7f800000
	v_mov_b32_e32 v65, 0x1000
	v_cndmask_b32_e64 v66, 0, 1, s[0:1]
	s_mov_b32 s58, s36
	s_mov_b32 s59, s36
	s_cmpk_lg_i32 s96, 0x100
	s_cbranch_scc1 .Ltr_keep
	s_addk_i32 s58, 0x1800
	s_addk_i32 s59, 0x1800
.Ltr_keep:
	v_readlane_b32 s16, v251, 8
	v_readlane_b32 s17, v251, 9
	v_readlane_b32 s18, v251, 10
	v_readlane_b32 s19, v251, 11
	s_branch .LBB0_9
